# HGRN chunk prefix sum: eight LDS reads issued together, same 16 dependent adds in order with counted waits
# speedup vs baseline: 1.0087x; 1.0087x over previous
; DI float bflo(unsigned w) { return __uint_as_float(w << 16); }
; DI float bfhi(unsigned w) { return __uint_as_float(w & 0xffff0000u); }
; DI float hflo(unsigned w) { return (float)__builtin_bit_cast(_Float16, (u16)(w & 0xffffu)); }
; DI float hfhi(unsigned w) { return (float)__builtin_bit_cast(_Float16, (u16)(w >> 16)); }
; DI void hgrn_unit(const P& p, int l, int unit, char* lds_all) {
;     ...
;   for (int c = 0; c < 36; ++c) {
;     int base;
;     if (c < 4) base = 2048 + (dir ? (3 - c) : c) * 64;
;     else base = (dir ? (31 - (c - 4)) : (c - 4)) * 64;
;     const int tok = base + (dir ? 63 - tau : tau);
;     float qv[16], kk[16];
;     {
;       const uint4* qp = (const uint4*)(qs + (size_t)tok * 64 + kc);
;       const uint4* zp = (const uint4*)(zs + (size_t)tok * 64 + kc);
;       const uint4* vp = (const uint4*)(is + (size_t)tok * 64 + kc);
;       const uint4 q0 = qp[0], q1 = qp[1], z0 = zp[0], z1 = zp[1], v0 = vp[0], v1 = vp[1];
;       const unsigned qw[8] = {q0.x, q0.y, q0.z, q0.w, q1.x, q1.y, q1.z, q1.w};
;       const unsigned zw[8] = {z0.x, z0.y, z0.z, z0.w, z1.x, z1.y, z1.z, z1.w};
;       const unsigned vw[8] = {v0.x, v0.y, v0.z, v0.w, v1.x, v1.y, v1.z, v1.w};
; #pragma unroll
;       for (int e = 0; e < 8; ++e) {
;         qv[2 * e] = bflo(qw[e]);
;         qv[2 * e + 1] = bfhi(qw[e]);
;         const float za = hflo(zw[e]), zb = hfhi(zw[e]);
;         const float fa = lbv[2 * e] + (1.f - lbv[2 * e]) / (1.f + __expf(-za));
;         const float fb = lbv[2 * e + 1] + (1.f - lbv[2 * e + 1]) / (1.f + __expf(-zb));
;         kk[2 * e] = 1.f - fa;
;         kk[2 * e + 1] = 1.f - fb;
;         Lf[tau * 65 + kc + 2 * e] = __logf(fa);
;         Lf[tau * 65 + kc + 2 * e + 1] = __logf(fb);
;         Vt[(kc + 2 * e) * 72 + tau] = (u16)(vw[e] & 0xffffu);
;         Vt[(kc + 2 * e + 1) * 72 + tau] = (u16)(vw[e] >> 16);
;       }
;     }
.LBB0_933:
	v_add_u32_e32 v2, v127, v99
	v_ashrrev_i32_e32 v3, 31, v2
	v_lshlrev_b64 v[2:3], 7, v[2:3]
	v_lshl_add_u64 v[4:5], v[44:45], 0, v[2:3]
	v_lshl_add_u64 v[6:7], v[46:47], 0, v[2:3]
	v_lshl_add_u64 v[12:13], v[48:49], 0, v[2:3]
	global_load_dwordx4 v[94:97], v[4:5], off offset:16
	global_load_dwordx4 v[8:11], v[4:5], off
	global_load_dwordx4 v[128:131], v[6:7], off offset:16
	global_load_dwordx4 v[14:17], v[6:7], off
	s_nop 0
	global_load_dwordx4 v[2:5], v[12:13], off offset:16
	global_load_dwordx4 v[18:21], v[12:13], off
	s_add_i32 s26, s26, -1
	s_add_i32 s24, s24, 1
	s_cmp_eq_u32 s26, -1
	s_waitcnt vmcnt(0)
	ds_write_b16 v103, v18 offset:45312
	ds_write_b16_d16_hi v104, v18 offset:45456
	v_lshlrev_b32_e32 v6, 16, v8
	v_and_b32_e32 v7, 0xffff0000, v8
	v_cvt_f32_f16_e32 v8, v14
	v_cvt_f32_f16_sdwa v12, v14 dst_sel:DWORD dst_unused:UNUSED_PAD src0_sel:WORD_1
	v_and_b32_e32 v13, 0xffff0000, v9
	ds_write_b16 v104, v19 offset:45600
	ds_write_b16_d16_hi v105, v19 offset:45456
	v_mul_f32_e32 v8, 0xbfb8aa3b, v8
	v_exp_f32_e32 v92, v8
	v_mul_f32_e32 v8, 0xbfb8aa3b, v12
	v_exp_f32_e32 v93, v8
	v_cvt_f32_f16_e32 v8, v15
	v_lshlrev_b32_e32 v12, 16, v9
	v_cvt_f32_f16_sdwa v9, v15 dst_sel:DWORD dst_unused:UNUSED_PAD src0_sel:WORD_1
	ds_write_b16 v105, v20 offset:45600
	ds_write_b16_d16_hi v106, v20 offset:45456
	v_mul_f32_e32 v8, 0xbfb8aa3b, v8
	v_exp_f32_e32 v14, v8
	v_mul_f32_e32 v8, 0xbfb8aa3b, v9
	v_exp_f32_e32 v15, v8
	v_cvt_f32_f16_e32 v8, v16
	v_cvt_f32_f16_sdwa v9, v16 dst_sel:DWORD dst_unused:UNUSED_PAD src0_sel:WORD_1
	ds_write_b16 v106, v21 offset:45600
	ds_write_b16_d16_hi v107, v21 offset:45456
	ds_write_b16 v107, v2 offset:45600
	ds_write_b16_d16_hi v108, v2 offset:45456
	v_mul_f32_e32 v8, 0xbfb8aa3b, v8
	v_exp_f32_e32 v90, v8
	v_mul_f32_e32 v8, 0xbfb8aa3b, v9
	v_exp_f32_e32 v91, v8
	v_cvt_f32_f16_e32 v8, v17
	v_cvt_f32_f16_sdwa v9, v17 dst_sel:DWORD dst_unused:UNUSED_PAD src0_sel:WORD_1
	v_cvt_f32_f16_e32 v2, v129
	ds_write_b16 v108, v3 offset:45600
	ds_write_b16_d16_hi v109, v3 offset:45456
	v_mul_f32_e32 v8, 0xbfb8aa3b, v8
	v_exp_f32_e32 v88, v8
	v_mul_f32_e32 v8, 0xbfb8aa3b, v9
	v_exp_f32_e32 v89, v8
	v_cvt_f32_f16_e32 v8, v128
	v_cvt_f32_f16_sdwa v9, v128 dst_sel:DWORD dst_unused:UNUSED_PAD src0_sel:WORD_1
	v_mul_f32_e32 v2, 0xbfb8aa3b, v2
	v_exp_f32_e32 v16, v2
	v_mul_f32_e32 v8, 0xbfb8aa3b, v8
	v_exp_f32_e32 v18, v8
	v_mul_f32_e32 v8, 0xbfb8aa3b, v9
	v_exp_f32_e32 v19, v8
	v_cvt_f32_f16_sdwa v8, v129 dst_sel:DWORD dst_unused:UNUSED_PAD src0_sel:WORD_1
	v_cvt_f32_f16_sdwa v3, v130 dst_sel:DWORD dst_unused:UNUSED_PAD src0_sel:WORD_1
	v_lshlrev_b32_e32 v26, 16, v10
	v_and_b32_e32 v27, 0xffff0000, v10
	v_mul_f32_e32 v2, 0xbfb8aa3b, v8
	v_exp_f32_e32 v17, v2
	v_cvt_f32_f16_e32 v2, v130
	v_lshlrev_b32_e32 v24, 16, v11
	v_and_b32_e32 v25, 0xffff0000, v11
	ds_write_b16 v109, v4 offset:45600
	ds_write_b16_d16_hi v110, v4 offset:45456
	v_mul_f32_e32 v2, 0xbfb8aa3b, v2
	v_exp_f32_e32 v10, v2
	v_mul_f32_e32 v2, 0xbfb8aa3b, v3
	v_exp_f32_e32 v11, v2
	v_cvt_f32_f16_e32 v2, v131
	v_cvt_f32_f16_sdwa v3, v131 dst_sel:DWORD dst_unused:UNUSED_PAD src0_sel:WORD_1
	ds_write_b16 v110, v5 offset:45600
	ds_write_b16_d16_hi v111, v5 offset:45456
	v_lshlrev_b32_e32 v22, 16, v94
	v_mul_f32_e32 v2, 0xbfb8aa3b, v2
	v_exp_f32_e32 v8, v2
	v_mul_f32_e32 v2, 0xbfb8aa3b, v3
	v_exp_f32_e32 v9, v2
	v_pk_add_f32 v[2:3], v[92:93], 1.0 op_sel_hi:[1,0]
	v_and_b32_e32 v23, 0xffff0000, v94
	v_div_scale_f32 v4, s[82:83], v3, v3, v53
	v_rcp_f32_e32 v5, v4
	v_pk_add_f32 v[88:89], v[88:89], 1.0 op_sel_hi:[1,0]
	v_pk_add_f32 v[18:19], v[18:19], 1.0 op_sel_hi:[1,0]
	v_lshlrev_b32_e32 v20, 16, v95
	v_fma_f32 v92, -v4, v5, 1.0
	v_fmac_f32_e32 v5, v92, v5
	v_div_scale_f32 v92, vcc, v53, v3, v53
	v_mul_f32_e32 v93, v92, v5
	v_fma_f32 v94, -v4, v93, v92
	v_fmac_f32_e32 v93, v94, v5
	v_fma_f32 v4, -v4, v93, v92
	v_div_fmas_f32 v4, v4, v5, v93
	v_div_fixup_f32 v3, v4, v3, v53
	v_div_scale_f32 v4, s[82:83], v2, v2, v52
	v_rcp_f32_e32 v5, v4
	v_and_b32_e32 v21, 0xffff0000, v95
	v_pk_add_f32 v[16:17], v[16:17], 1.0 op_sel_hi:[1,0]
	v_lshlrev_b32_e32 v86, 16, v96
	v_fma_f32 v92, -v4, v5, 1.0
	v_fmac_f32_e32 v5, v92, v5
	v_div_scale_f32 v92, vcc, v52, v2, v52
	v_mul_f32_e32 v93, v92, v5
	v_fma_f32 v94, -v4, v93, v92
	v_fmac_f32_e32 v93, v94, v5
	v_fma_f32 v4, -v4, v93, v92
	v_div_fmas_f32 v4, v4, v5, v93
	v_div_fixup_f32 v2, v4, v2, v52
	v_pk_add_f32 v[4:5], v[28:29], v[2:3]
	v_and_b32_e32 v87, 0xffff0000, v96
	v_cmp_gt_f32_e32 vcc, s37, v4
	v_pk_add_f32 v[2:3], v[4:5], 1.0 op_sel_hi:[1,0] neg_lo:[1,0] neg_hi:[1,0]
	v_lshlrev_b32_e32 v84, 16, v97
	v_cndmask_b32_e64 v92, 0, 32, vcc
	v_ldexp_f32 v4, v4, v92
	v_log_f32_e32 v4, v4
	v_and_b32_e32 v85, 0xffff0000, v97
	v_pk_add_f32 v[10:11], v[10:11], 1.0 op_sel_hi:[1,0]
	v_pk_add_f32 v[8:9], v[8:9], 1.0 op_sel_hi:[1,0]
	v_mul_f32_e32 v92, 0x3f317217, v4
	v_fma_f32 v92, v4, s22, -v92
	v_fmac_f32_e32 v92, 0x3377d1cf, v4
	v_fmac_f32_e32 v92, 0x3f317217, v4
	v_cmp_lt_f32_e64 s[82:83], |v4|, s31
	s_nop 1
	v_cndmask_b32_e64 v4, v4, v92, s[82:83]
	v_cndmask_b32_e32 v92, 0, v225, vcc
	v_cmp_gt_f32_e32 vcc, s37, v5
	v_sub_f32_e32 v4, v4, v92
	s_nop 0
	v_cndmask_b32_e64 v92, 0, 32, vcc
	v_ldexp_f32 v5, v5, v92
	v_log_f32_e32 v5, v5
	s_nop 0
	v_mul_f32_e32 v92, 0x3f317217, v5
	v_fma_f32 v92, v5, s22, -v92
	v_fmac_f32_e32 v92, 0x3377d1cf, v5
	v_fmac_f32_e32 v92, 0x3f317217, v5
	v_cmp_lt_f32_e64 s[82:83], |v5|, s31
	s_nop 1
	v_cndmask_b32_e64 v5, v5, v92, s[82:83]
	v_cndmask_b32_e32 v92, 0, v225, vcc
	v_sub_f32_e32 v5, v5, v92
	ds_write2_b32 v100, v4, v5 offset1:1
	v_pk_add_f32 v[4:5], v[14:15], 1.0 op_sel_hi:[1,0]
	s_nop 0
; DI float bflo(unsigned w) { return __uint_as_float(w << 16); }
; DI float bfhi(unsigned w) { return __uint_as_float(w & 0xffff0000u); }
; DI float hflo(unsigned w) { return (float)__builtin_bit_cast(_Float16, (u16)(w & 0xffffu)); }
; DI float hfhi(unsigned w) { return (float)__builtin_bit_cast(_Float16, (u16)(w >> 16)); }
; DI void hgrn_unit(const P& p, int l, int unit, char* lds_all) {
;     ...
;       for (int e = 0; e < 8; ++e) {
;         qv[2 * e] = bflo(qw[e]);
;         qv[2 * e + 1] = bfhi(qw[e]);
;         const float za = hflo(zw[e]), zb = hfhi(zw[e]);
;         const float fa = lbv[2 * e] + (1.f - lbv[2 * e]) / (1.f + __expf(-za));
;         const float fb = lbv[2 * e + 1] + (1.f - lbv[2 * e + 1]) / (1.f + __expf(-zb));
;         kk[2 * e] = 1.f - fa;
;         kk[2 * e + 1] = 1.f - fb;
;         Lf[tau * 65 + kc + 2 * e] = __logf(fa);
;         Lf[tau * 65 + kc + 2 * e + 1] = __logf(fb);
	v_div_scale_f32 v14, s[82:83], v5, v5, v55
	v_rcp_f32_e32 v15, v14
	s_nop 0
	v_fma_f32 v92, -v14, v15, 1.0
	v_fmac_f32_e32 v15, v92, v15
	v_div_scale_f32 v92, vcc, v55, v5, v55
	v_mul_f32_e32 v93, v92, v15
	v_fma_f32 v94, -v14, v93, v92
	v_fmac_f32_e32 v93, v94, v15
	v_fma_f32 v14, -v14, v93, v92
	v_div_fmas_f32 v14, v14, v15, v93
	v_div_fixup_f32 v5, v14, v5, v55
	v_div_scale_f32 v14, s[82:83], v4, v4, v54
	v_rcp_f32_e32 v15, v14
	s_nop 0
	v_fma_f32 v92, -v14, v15, 1.0
	v_fmac_f32_e32 v15, v92, v15
	v_div_scale_f32 v92, vcc, v54, v4, v54
	v_mul_f32_e32 v93, v92, v15
	v_fma_f32 v94, -v14, v93, v92
	v_fmac_f32_e32 v93, v94, v15
	v_fma_f32 v14, -v14, v93, v92
	v_div_fmas_f32 v14, v14, v15, v93
	v_div_fixup_f32 v4, v14, v4, v54
	v_pk_add_f32 v[4:5], v[30:31], v[4:5]
	s_nop 0
	v_cmp_gt_f32_e32 vcc, s37, v4
	v_pk_add_f32 v[14:15], v[4:5], 1.0 op_sel_hi:[1,0] neg_lo:[1,0] neg_hi:[1,0]
	s_nop 0
	v_cndmask_b32_e64 v92, 0, 32, vcc
	v_ldexp_f32 v4, v4, v92
	v_log_f32_e32 v4, v4
	s_nop 0
	v_mul_f32_e32 v92, 0x3f317217, v4
	v_fma_f32 v92, v4, s22, -v92
	v_fmac_f32_e32 v92, 0x3377d1cf, v4
	v_fmac_f32_e32 v92, 0x3f317217, v4
	v_cmp_lt_f32_e64 s[82:83], |v4|, s31
	s_nop 1
	v_cndmask_b32_e64 v4, v4, v92, s[82:83]
	v_cndmask_b32_e32 v92, 0, v225, vcc
	v_cmp_gt_f32_e32 vcc, s37, v5
	v_sub_f32_e32 v4, v4, v92
	s_nop 0
	v_cndmask_b32_e64 v92, 0, 32, vcc
	v_ldexp_f32 v5, v5, v92
	v_log_f32_e32 v5, v5
	s_nop 0
	v_mul_f32_e32 v92, 0x3f317217, v5
	v_fma_f32 v92, v5, s22, -v92
	v_fmac_f32_e32 v92, 0x3377d1cf, v5
	v_fmac_f32_e32 v92, 0x3f317217, v5
	v_cmp_lt_f32_e64 s[82:83], |v5|, s31
	s_nop 1
	v_cndmask_b32_e64 v5, v5, v92, s[82:83]
	v_cndmask_b32_e32 v92, 0, v225, vcc
	v_sub_f32_e32 v5, v5, v92
	ds_write2_b32 v100, v4, v5 offset0:2 offset1:3
	v_pk_add_f32 v[4:5], v[90:91], 1.0 op_sel_hi:[1,0]
	s_nop 0
	v_div_scale_f32 v90, s[82:83], v5, v5, v57
	v_rcp_f32_e32 v91, v90
	s_nop 0
	v_fma_f32 v92, -v90, v91, 1.0
	v_fmac_f32_e32 v91, v92, v91
	v_div_scale_f32 v92, vcc, v57, v5, v57
	v_mul_f32_e32 v93, v92, v91
	v_fma_f32 v94, -v90, v93, v92
	v_fmac_f32_e32 v93, v94, v91
	v_fma_f32 v90, -v90, v93, v92
	v_div_fmas_f32 v90, v90, v91, v93
	v_div_fixup_f32 v5, v90, v5, v57
	v_div_scale_f32 v90, s[82:83], v4, v4, v56
	v_rcp_f32_e32 v91, v90
	s_nop 0
	v_fma_f32 v92, -v90, v91, 1.0
	v_fmac_f32_e32 v91, v92, v91
	v_div_scale_f32 v92, vcc, v56, v4, v56
	v_mul_f32_e32 v93, v92, v91
	v_fma_f32 v94, -v90, v93, v92
	v_fmac_f32_e32 v93, v94, v91
	v_fma_f32 v90, -v90, v93, v92
	v_div_fmas_f32 v90, v90, v91, v93
	v_div_fixup_f32 v4, v90, v4, v56
	v_pk_add_f32 v[90:91], v[32:33], v[4:5]
	s_nop 0
	v_cmp_gt_f32_e32 vcc, s37, v90
	v_pk_add_f32 v[4:5], v[90:91], 1.0 op_sel_hi:[1,0] neg_lo:[1,0] neg_hi:[1,0]
	s_nop 0
	v_cndmask_b32_e64 v92, 0, 32, vcc
	v_ldexp_f32 v90, v90, v92
	v_log_f32_e32 v90, v90
	s_nop 0
	v_mul_f32_e32 v92, 0x3f317217, v90
	v_fma_f32 v92, v90, s22, -v92
	v_fmac_f32_e32 v92, 0x3377d1cf, v90
	v_fmac_f32_e32 v92, 0x3f317217, v90
	v_cmp_lt_f32_e64 s[82:83], |v90|, s31
	s_nop 1
	v_cndmask_b32_e64 v90, v90, v92, s[82:83]
	v_cndmask_b32_e32 v92, 0, v225, vcc
	v_cmp_gt_f32_e32 vcc, s37, v91
	v_sub_f32_e32 v90, v90, v92
	s_nop 0
	v_cndmask_b32_e64 v92, 0, 32, vcc
	v_ldexp_f32 v91, v91, v92
	v_log_f32_e32 v91, v91
	s_nop 0
	v_mul_f32_e32 v92, 0x3f317217, v91
	v_fma_f32 v92, v91, s22, -v92
	v_fmac_f32_e32 v92, 0x3377d1cf, v91
	v_fmac_f32_e32 v92, 0x3f317217, v91
	v_cmp_lt_f32_e64 s[82:83], |v91|, s31
	s_nop 1
	v_cndmask_b32_e64 v91, v91, v92, s[82:83]
	v_cndmask_b32_e32 v92, 0, v225, vcc
	v_sub_f32_e32 v91, v91, v92
	ds_write2_b32 v100, v90, v91 offset0:4 offset1:5
	v_div_scale_f32 v90, s[82:83], v89, v89, v59
	v_rcp_f32_e32 v91, v90
	s_nop 0
	v_fma_f32 v92, -v90, v91, 1.0
	v_fmac_f32_e32 v91, v92, v91
	v_div_scale_f32 v92, vcc, v59, v89, v59
	v_mul_f32_e32 v93, v92, v91
	v_fma_f32 v94, -v90, v93, v92
	v_fmac_f32_e32 v93, v94, v91
	v_fma_f32 v90, -v90, v93, v92
	v_div_fmas_f32 v90, v90, v91, v93
	v_div_fixup_f32 v89, v90, v89, v59
	v_div_scale_f32 v90, s[82:83], v88, v88, v58
	v_rcp_f32_e32 v91, v90
	s_nop 0
	v_fma_f32 v92, -v90, v91, 1.0
	v_fmac_f32_e32 v91, v92, v91
	v_div_scale_f32 v92, vcc, v58, v88, v58
	v_mul_f32_e32 v93, v92, v91
	v_fma_f32 v94, -v90, v93, v92
	v_fmac_f32_e32 v93, v94, v91
	v_fma_f32 v90, -v90, v93, v92
	v_div_fmas_f32 v90, v90, v91, v93
	v_div_fixup_f32 v88, v90, v88, v58
	v_pk_add_f32 v[88:89], v[34:35], v[88:89]
	s_nop 0
	v_cmp_gt_f32_e32 vcc, s37, v88
	v_pk_add_f32 v[90:91], v[88:89], 1.0 op_sel_hi:[1,0] neg_lo:[1,0] neg_hi:[1,0]
	s_nop 0
	v_cndmask_b32_e64 v92, 0, 32, vcc
	v_ldexp_f32 v88, v88, v92
	v_log_f32_e32 v88, v88
	s_nop 0
	v_mul_f32_e32 v92, 0x3f317217, v88
	v_fma_f32 v92, v88, s22, -v92
	v_fmac_f32_e32 v92, 0x3377d1cf, v88
	v_fmac_f32_e32 v92, 0x3f317217, v88
	v_cmp_lt_f32_e64 s[82:83], |v88|, s31
	s_nop 1
	v_cndmask_b32_e64 v88, v88, v92, s[82:83]
	v_cndmask_b32_e32 v92, 0, v225, vcc
	v_cmp_gt_f32_e32 vcc, s37, v89
	v_sub_f32_e32 v88, v88, v92
	s_nop 0
	v_cndmask_b32_e64 v92, 0, 32, vcc
	v_ldexp_f32 v89, v89, v92
	v_log_f32_e32 v89, v89
	s_nop 0
	v_mul_f32_e32 v92, 0x3f317217, v89
	v_fma_f32 v92, v89, s22, -v92
	v_fmac_f32_e32 v92, 0x3377d1cf, v89
	v_fmac_f32_e32 v92, 0x3f317217, v89
	v_cmp_lt_f32_e64 s[82:83], |v89|, s31
	s_nop 1
	v_cndmask_b32_e64 v89, v89, v92, s[82:83]
	v_cndmask_b32_e32 v92, 0, v225, vcc
	v_sub_f32_e32 v89, v89, v92
	ds_write2_b32 v100, v88, v89 offset0:6 offset1:7
	v_div_scale_f32 v88, s[82:83], v19, v19, v61
	v_rcp_f32_e32 v89, v88
	s_nop 0
	v_fma_f32 v92, -v88, v89, 1.0
	v_fmac_f32_e32 v89, v92, v89
	v_div_scale_f32 v92, vcc, v61, v19, v61
	v_mul_f32_e32 v93, v92, v89
	v_fma_f32 v94, -v88, v93, v92
; DI float bflo(unsigned w) { return __uint_as_float(w << 16); }
; DI float bfhi(unsigned w) { return __uint_as_float(w & 0xffff0000u); }
; DI float hflo(unsigned w) { return (float)__builtin_bit_cast(_Float16, (u16)(w & 0xffffu)); }
; DI float hfhi(unsigned w) { return (float)__builtin_bit_cast(_Float16, (u16)(w >> 16)); }
; DI void hgrn_unit(const P& p, int l, int unit, char* lds_all) {
;     ...
; #pragma unroll
;       for (int e = 0; e < 8; ++e) {
;         qv[2 * e] = bflo(qw[e]);
;         qv[2 * e + 1] = bfhi(qw[e]);
;         const float za = hflo(zw[e]), zb = hfhi(zw[e]);
;         const float fa = lbv[2 * e] + (1.f - lbv[2 * e]) / (1.f + __expf(-za));
;         const float fb = lbv[2 * e + 1] + (1.f - lbv[2 * e + 1]) / (1.f + __expf(-zb));
;         kk[2 * e] = 1.f - fa;
;         kk[2 * e + 1] = 1.f - fb;
;         Lf[tau * 65 + kc + 2 * e] = __logf(fa);
;         Lf[tau * 65 + kc + 2 * e + 1] = __logf(fb);
;         Vt[(kc + 2 * e) * 72 + tau] = (u16)(vw[e] & 0xffffu);
;         Vt[(kc + 2 * e + 1) * 72 + tau] = (u16)(vw[e] >> 16);
;       }
;     }
;     __syncthreads();
	v_fmac_f32_e32 v93, v94, v89
	v_fma_f32 v88, -v88, v93, v92
	v_div_fmas_f32 v88, v88, v89, v93
	v_div_fixup_f32 v19, v88, v19, v61
	v_div_scale_f32 v88, s[82:83], v18, v18, v60
	v_rcp_f32_e32 v89, v88
	s_nop 0
	v_fma_f32 v92, -v88, v89, 1.0
	v_fmac_f32_e32 v89, v92, v89
	v_div_scale_f32 v92, vcc, v60, v18, v60
	v_mul_f32_e32 v93, v92, v89
	v_fma_f32 v94, -v88, v93, v92
	v_fmac_f32_e32 v93, v94, v89
	v_fma_f32 v88, -v88, v93, v92
	v_div_fmas_f32 v88, v88, v89, v93
	v_div_fixup_f32 v18, v88, v18, v60
	v_pk_add_f32 v[18:19], v[36:37], v[18:19]
	s_nop 0
	v_cmp_gt_f32_e32 vcc, s37, v18
	v_pk_add_f32 v[94:95], v[18:19], 1.0 op_sel_hi:[1,0] neg_lo:[1,0] neg_hi:[1,0]
	s_nop 0
	v_cndmask_b32_e64 v88, 0, 32, vcc
	v_ldexp_f32 v18, v18, v88
	v_log_f32_e32 v18, v18
	s_nop 0
	v_mul_f32_e32 v88, 0x3f317217, v18
	v_fma_f32 v88, v18, s22, -v88
	v_fmac_f32_e32 v88, 0x3377d1cf, v18
	v_fmac_f32_e32 v88, 0x3f317217, v18
	v_cmp_lt_f32_e64 s[82:83], |v18|, s31
	s_nop 1
	v_cndmask_b32_e64 v18, v18, v88, s[82:83]
	v_cndmask_b32_e32 v88, 0, v225, vcc
	v_cmp_gt_f32_e32 vcc, s37, v19
	v_sub_f32_e32 v18, v18, v88
	s_nop 0
	v_cndmask_b32_e64 v88, 0, 32, vcc
	v_ldexp_f32 v19, v19, v88
	v_log_f32_e32 v19, v19
	s_nop 0
	v_mul_f32_e32 v88, 0x3f317217, v19
	v_fma_f32 v88, v19, s22, -v88
	v_fmac_f32_e32 v88, 0x3377d1cf, v19
	v_fmac_f32_e32 v88, 0x3f317217, v19
	v_cmp_lt_f32_e64 s[82:83], |v19|, s31
	s_nop 1
	v_cndmask_b32_e64 v19, v19, v88, s[82:83]
	v_cndmask_b32_e32 v88, 0, v225, vcc
	v_sub_f32_e32 v19, v19, v88
	ds_write2_b32 v100, v18, v19 offset0:8 offset1:9
	v_div_scale_f32 v18, s[82:83], v17, v17, v63
	v_rcp_f32_e32 v19, v18
	s_nop 0
	v_fma_f32 v88, -v18, v19, 1.0
	v_fmac_f32_e32 v19, v88, v19
	v_div_scale_f32 v88, vcc, v63, v17, v63
	v_mul_f32_e32 v89, v88, v19
	v_fma_f32 v92, -v18, v89, v88
	v_fmac_f32_e32 v89, v92, v19
	v_fma_f32 v18, -v18, v89, v88
	v_div_fmas_f32 v18, v18, v19, v89
	v_div_fixup_f32 v17, v18, v17, v63
	v_div_scale_f32 v18, s[82:83], v16, v16, v62
	v_rcp_f32_e32 v19, v18
	s_nop 0
	v_fma_f32 v88, -v18, v19, 1.0
	v_fmac_f32_e32 v19, v88, v19
	v_div_scale_f32 v88, vcc, v62, v16, v62
	v_mul_f32_e32 v89, v88, v19
	v_fma_f32 v92, -v18, v89, v88
	v_fmac_f32_e32 v89, v92, v19
	v_fma_f32 v18, -v18, v89, v88
	v_div_fmas_f32 v18, v18, v19, v89
	v_div_fixup_f32 v16, v18, v16, v62
	v_pk_add_f32 v[16:17], v[38:39], v[16:17]
	s_nop 0
	v_cmp_gt_f32_e32 vcc, s37, v16
	v_pk_add_f32 v[96:97], v[16:17], 1.0 op_sel_hi:[1,0] neg_lo:[1,0] neg_hi:[1,0]
	s_nop 0
	v_cndmask_b32_e64 v18, 0, 32, vcc
	v_ldexp_f32 v16, v16, v18
	v_log_f32_e32 v16, v16
	s_nop 0
	v_mul_f32_e32 v18, 0x3f317217, v16
	v_fma_f32 v18, v16, s22, -v18
	v_fmac_f32_e32 v18, 0x3377d1cf, v16
	v_fmac_f32_e32 v18, 0x3f317217, v16
	v_cmp_lt_f32_e64 s[82:83], |v16|, s31
	s_nop 1
	v_cndmask_b32_e64 v16, v16, v18, s[82:83]
	v_cndmask_b32_e32 v18, 0, v225, vcc
	v_cmp_gt_f32_e32 vcc, s37, v17
	v_sub_f32_e32 v16, v16, v18
	s_nop 0
	v_cndmask_b32_e64 v18, 0, 32, vcc
	v_ldexp_f32 v17, v17, v18
	v_log_f32_e32 v17, v17
	s_nop 0
	v_mul_f32_e32 v18, 0x3f317217, v17
	v_fma_f32 v18, v17, s22, -v18
	v_fmac_f32_e32 v18, 0x3377d1cf, v17
	v_fmac_f32_e32 v18, 0x3f317217, v17
	v_cmp_lt_f32_e64 s[82:83], |v17|, s31
	s_nop 1
	v_cndmask_b32_e64 v17, v17, v18, s[82:83]
	v_cndmask_b32_e32 v18, 0, v225, vcc
	v_sub_f32_e32 v17, v17, v18
	ds_write2_b32 v100, v16, v17 offset0:10 offset1:11
	v_div_scale_f32 v16, s[82:83], v11, v11, v65
	v_rcp_f32_e32 v17, v16
	s_nop 0
	v_fma_f32 v18, -v16, v17, 1.0
	v_fmac_f32_e32 v17, v18, v17
	v_div_scale_f32 v18, vcc, v65, v11, v65
	v_mul_f32_e32 v19, v18, v17
	v_fma_f32 v88, -v16, v19, v18
	v_fmac_f32_e32 v19, v88, v17
	v_fma_f32 v16, -v16, v19, v18
	v_div_fmas_f32 v16, v16, v17, v19
	v_div_fixup_f32 v11, v16, v11, v65
	v_div_scale_f32 v16, s[82:83], v10, v10, v64
	v_rcp_f32_e32 v17, v16
	s_nop 0
	v_fma_f32 v18, -v16, v17, 1.0
	v_fmac_f32_e32 v17, v18, v17
	v_div_scale_f32 v18, vcc, v64, v10, v64
	v_mul_f32_e32 v19, v18, v17
	v_fma_f32 v88, -v16, v19, v18
	v_fmac_f32_e32 v19, v88, v17
	v_fma_f32 v16, -v16, v19, v18
	v_div_fmas_f32 v16, v16, v17, v19
	v_div_fixup_f32 v10, v16, v10, v64
	v_pk_add_f32 v[10:11], v[40:41], v[10:11]
	s_nop 0
	v_cmp_gt_f32_e32 vcc, s37, v10
	v_pk_add_f32 v[92:93], v[10:11], 1.0 op_sel_hi:[1,0] neg_lo:[1,0] neg_hi:[1,0]
	s_nop 0
	v_cndmask_b32_e64 v16, 0, 32, vcc
	v_ldexp_f32 v10, v10, v16
	v_log_f32_e32 v10, v10
	s_nop 0
	v_mul_f32_e32 v16, 0x3f317217, v10
	v_fma_f32 v16, v10, s22, -v16
	v_fmac_f32_e32 v16, 0x3377d1cf, v10
	v_fmac_f32_e32 v16, 0x3f317217, v10
	v_cmp_lt_f32_e64 s[82:83], |v10|, s31
	s_nop 1
	v_cndmask_b32_e64 v10, v10, v16, s[82:83]
	v_cndmask_b32_e32 v16, 0, v225, vcc
	v_cmp_gt_f32_e32 vcc, s37, v11
	v_sub_f32_e32 v10, v10, v16
	s_nop 0
	v_cndmask_b32_e64 v16, 0, 32, vcc
	v_ldexp_f32 v11, v11, v16
	v_log_f32_e32 v11, v11
	s_nop 0
	v_mul_f32_e32 v16, 0x3f317217, v11
	v_fma_f32 v16, v11, s22, -v16
	v_fmac_f32_e32 v16, 0x3377d1cf, v11
	v_fmac_f32_e32 v16, 0x3f317217, v11
	v_cmp_lt_f32_e64 s[82:83], |v11|, s31
	s_nop 1
	v_cndmask_b32_e64 v11, v11, v16, s[82:83]
	v_cndmask_b32_e32 v16, 0, v225, vcc
	v_sub_f32_e32 v11, v11, v16
	ds_write2_b32 v100, v10, v11 offset0:12 offset1:13
	v_div_scale_f32 v10, s[82:83], v9, v9, v67
	v_rcp_f32_e32 v11, v10
	s_nop 0
	v_fma_f32 v16, -v10, v11, 1.0
	v_fmac_f32_e32 v11, v16, v11
	v_div_scale_f32 v16, vcc, v67, v9, v67
	v_mul_f32_e32 v17, v16, v11
	v_fma_f32 v18, -v10, v17, v16
	v_fmac_f32_e32 v17, v18, v11
	v_fma_f32 v10, -v10, v17, v16
	v_div_fmas_f32 v10, v10, v11, v17
	v_div_fixup_f32 v9, v10, v9, v67
	v_div_scale_f32 v10, s[82:83], v8, v8, v66
	v_rcp_f32_e32 v11, v10
	s_nop 0
	v_fma_f32 v16, -v10, v11, 1.0
	v_fmac_f32_e32 v11, v16, v11
	v_div_scale_f32 v16, vcc, v66, v8, v66
	v_mul_f32_e32 v17, v16, v11
	v_fma_f32 v18, -v10, v17, v16
	v_fmac_f32_e32 v17, v18, v11
	v_fma_f32 v10, -v10, v17, v16
	v_div_fmas_f32 v10, v10, v11, v17
	v_div_fixup_f32 v8, v10, v8, v66
	v_pk_add_f32 v[8:9], v[42:43], v[8:9]
	v_add_u32_e32 v11, 0x400, v118
	v_cmp_gt_f32_e32 vcc, s37, v8
	v_pk_add_f32 v[88:89], v[8:9], 1.0 op_sel_hi:[1,0] neg_lo:[1,0] neg_hi:[1,0]
	s_nop 0
	v_cndmask_b32_e64 v10, 0, 32, vcc
	v_ldexp_f32 v8, v8, v10
	v_log_f32_e32 v8, v8
	s_nop 0
	v_mul_f32_e32 v10, 0x3f317217, v8
	v_fma_f32 v10, v8, s22, -v10
	v_fmac_f32_e32 v10, 0x3377d1cf, v8
	v_fmac_f32_e32 v10, 0x3f317217, v8
	v_cmp_lt_f32_e64 s[82:83], |v8|, s31
	s_nop 1
	v_cndmask_b32_e64 v8, v8, v10, s[82:83]
	v_cndmask_b32_e32 v10, 0, v225, vcc
	v_cmp_gt_f32_e32 vcc, s37, v9
	v_sub_f32_e32 v8, v8, v10
	s_nop 0
	v_cndmask_b32_e64 v10, 0, 32, vcc
	v_ldexp_f32 v9, v9, v10
	v_log_f32_e32 v9, v9
	s_nop 0
	v_mul_f32_e32 v10, 0x3f317217, v9
	v_fma_f32 v10, v9, s22, -v10
	v_fmac_f32_e32 v10, 0x3377d1cf, v9
	v_fmac_f32_e32 v10, 0x3f317217, v9
	v_cmp_lt_f32_e64 s[82:83], |v9|, s31
	s_nop 1
	v_cndmask_b32_e64 v9, v9, v10, s[82:83]
	v_cndmask_b32_e32 v10, 0, v225, vcc
	v_sub_f32_e32 v9, v9, v10
	ds_write2_b32 v100, v8, v9 offset0:14 offset1:15
	s_waitcnt lgkmcnt(0)
	s_barrier
; DI u16 f2bf(float x) { return (u16)pack2(x, 0.f); }
; DI void hgrn_unit(const P& p, int l, int unit, char* lds_all) {
;     ...
;     {
;       const int k = tid & 63, sg = tid >> 6;
;       float run = 0.f;
; #pragma unroll
;       for (int i = 0; i < 16; ++i) {
;         float* ptr = &Lf[(sg * 16 + i) * 65 + k];
;         run += *ptr;
;         *ptr = run;
;       }
;       Seg[sg * 64 + k] = run;
;     }
;     __syncthreads();
;     {
;       const int sg = tau >> 4;
;       unsigned qmw[8], kmw[8];
; #pragma unroll
;       for (int e = 0; e < 8; ++e) {
;         float qq[2], km2[2];
; #pragma unroll
;         for (int u = 0; u < 2; ++u) {
;           const int i = 2 * e + u, k = kc + i;
;           const float s0 = Seg[k], s1 = Seg[64 + k], s2 = Seg[128 + k];
;           const float off = (sg > 0 ? s0 : 0.f) + (sg > 1 ? s1 : 0.f) + (sg > 2 ? s2 : 0.f);
;           const float bc = Lf[tau * 65 + k] + off;
;           const float rr = Lf[31 * 65 + k] + s0;
;           qq[u] = qv[i] * __expf(bc - rr);
;           km2[u] = kk[i] * __expf(rr - bc);
;           KmT[k * 72 + tau] = f2bf(km2[u]);
;         }
;         qmw[e] = pack2(qq[0], qq[1]);
;         kmw[e] = pack2(km2[0], km2[1]);
;       }
;       *(uint4*)&Qm[tau * 72 + kc] = make_uint4(qmw[0], qmw[1], qmw[2], qmw[3]);
;       *(uint4*)&Qm[tau * 72 + kc + 8] = make_uint4(qmw[4], qmw[5], qmw[6], qmw[7]);
;       *(uint4*)&Km[tau * 72 + kc] = make_uint4(kmw[0], kmw[1], kmw[2], kmw[3]);
;       *(uint4*)&Km[tau * 72 + kc + 8] = make_uint4(kmw[4], kmw[5], kmw[6], kmw[7]);
	v_add_u32_e32 v160, 0x400, v118
	v_add_u32_e32 v161, 0x800, v118
	v_add_u32_e32 v162, 0xc00, v118
	ds_read2_b32 v[144:145], v118 offset1:65
	ds_read2_b32 v[146:147], v118 offset0:130 offset1:195
	ds_read2_b32 v[148:149], v160 offset0:4 offset1:69
	ds_read2_b32 v[150:151], v160 offset0:134 offset1:199
	ds_read2_b32 v[152:153], v161 offset0:8 offset1:73
	ds_read2_b32 v[154:155], v161 offset0:138 offset1:203
	ds_read2_b32 v[156:157], v162 offset0:12 offset1:77
	ds_read2_b32 v[158:159], v162 offset0:142 offset1:207
	s_waitcnt lgkmcnt(7)
	v_add_f32_e32 v144, 0, v144
	v_add_f32_e32 v145, v144, v145
	ds_write2_b32 v118, v144, v145 offset1:65
	s_waitcnt lgkmcnt(7)
	v_add_f32_e32 v146, v145, v146
	v_add_f32_e32 v147, v146, v147
	ds_write2_b32 v118, v146, v147 offset0:130 offset1:195
	s_waitcnt lgkmcnt(7)
	v_add_f32_e32 v148, v147, v148
	v_add_f32_e32 v149, v148, v149
	ds_write2_b32 v160, v148, v149 offset0:4 offset1:69
	s_waitcnt lgkmcnt(7)
	v_add_f32_e32 v150, v149, v150
	v_add_f32_e32 v151, v150, v151
	ds_write2_b32 v160, v150, v151 offset0:134 offset1:199
	s_waitcnt lgkmcnt(7)
	v_add_f32_e32 v152, v151, v152
	v_add_f32_e32 v153, v152, v153
	ds_write2_b32 v161, v152, v153 offset0:8 offset1:73
	s_waitcnt lgkmcnt(7)
	v_add_f32_e32 v154, v153, v154
	v_add_f32_e32 v155, v154, v155
	ds_write2_b32 v161, v154, v155 offset0:138 offset1:203
	s_waitcnt lgkmcnt(7)
	v_add_f32_e32 v156, v155, v156
	v_add_f32_e32 v157, v156, v157
	ds_write2_b32 v162, v156, v157 offset0:12 offset1:77
	s_waitcnt lgkmcnt(7)
	v_add_f32_e32 v158, v157, v158
	v_add_f32_e32 v159, v158, v159
	ds_write2_b32 v162, v158, v159 offset0:142 offset1:207
	ds_write_b32 v101, v159 offset:16640
	s_waitcnt lgkmcnt(0)
	s_barrier
	ds_read_b128 v[16:19], v112 offset:16640
	ds_read_b128 v[8:11], v112 offset:16656
	ds_read_b128 v[128:131], v112 offset:16896
	ds_read_b128 v[132:135], v112 offset:17152
	ds_read2_b32 v[138:139], v100 offset1:1
	s_waitcnt lgkmcnt(4)
	v_cndmask_b32_e64 v136, v16, 0, s[42:43]
	v_mov_b32_e32 v142, v16
	s_waitcnt lgkmcnt(2)
	v_cndmask_b32_e64 v128, 0, v128, s[44:45]
	v_add_f32_e32 v128, v136, v128
	s_waitcnt lgkmcnt(1)
	v_cndmask_b32_e64 v132, 0, v132, s[46:47]
	v_add_f32_e32 v137, v128, v132
	v_add_u32_e32 v128, 0x1f7c, v112
	ds_read2_b32 v[140:141], v128 offset1:1
	v_cndmask_b32_e64 v132, v17, 0, s[42:43]
	v_cndmask_b32_e64 v129, 0, v129, s[44:45]
	v_add_f32_e32 v129, v132, v129
	v_cndmask_b32_e64 v132, 0, v133, s[46:47]
	s_waitcnt lgkmcnt(1)
	v_mov_b32_e32 v143, v138
	s_waitcnt lgkmcnt(0)
	v_mov_b32_e32 v136, v140
	v_add_f32_e32 v133, v129, v132
	v_mov_b32_e32 v138, v17
	v_mov_b32_e32 v132, v141
	v_pk_add_f32 v[136:137], v[142:143], v[136:137]
	v_pk_add_f32 v[132:133], v[138:139], v[132:133]
	v_sub_f32_e32 v128, v136, v137
	v_sub_f32_e32 v17, v132, v133
	v_mul_f32_e32 v128, 0x3fb8aa3b, v128
	v_mul_f32_e32 v17, 0x3fb8aa3b, v17
	v_exp_f32_e32 v128, v128
	v_exp_f32_e32 v129, v17
	v_sub_f32_e32 v16, v137, v136
	v_mul_f32_e32 v16, 0x3fb8aa3b, v16
	v_exp_f32_e32 v16, v16
	v_pk_mul_f32 v[2:3], v[2:3], v[128:129]
	ds_read2_b32 v[128:129], v100 offset0:2 offset1:3
	v_cvt_pk_bf16_f32 v17, v2, s0
	ds_write_b16 v119, v17 offset:36096
	v_sub_f32_e32 v17, v133, v132
	v_mul_f32_e32 v17, 0x3fb8aa3b, v17
	v_exp_f32_e32 v17, v17
	v_cvt_pk_bf16_f32 v2, v2, v3
	v_mov_b32_e32 v136, v18
	v_pk_mul_f32 v[6:7], v[16:17], v[6:7]
	v_cvt_pk_bf16_f32 v16, v3, s0
	v_cvt_pk_bf16_f32 v6, v6, v7
	v_cndmask_b32_e64 v3, v18, 0, s[42:43]
	v_cndmask_b32_e64 v7, 0, v130, s[44:45]
	v_add_f32_e32 v3, v3, v7
	v_cndmask_b32_e64 v7, 0, v134, s[46:47]
	v_add_f32_e32 v17, v3, v7
	v_add_u32_e32 v3, 0x1f84, v112
	ds_read2_b32 v[132:133], v3 offset1:1
	ds_write_b16 v119, v16 offset:36240
	s_waitcnt lgkmcnt(3)
	v_mov_b32_e32 v137, v128
	v_cndmask_b32_e64 v7, 0, v131, s[44:45]
	v_mov_b32_e32 v128, v19
	s_waitcnt lgkmcnt(1)
	v_mov_b32_e32 v16, v132
	v_pk_add_f32 v[16:17], v[136:137], v[16:17]
	v_mov_b32_e32 v130, v133
	v_sub_f32_e32 v3, v17, v16
	v_mul_f32_e32 v3, 0x3fb8aa3b, v3
	v_exp_f32_e32 v18, v3
	v_sub_f32_e32 v3, v16, v17
	v_mul_f32_e32 v3, 0x3fb8aa3b, v3
	v_exp_f32_e32 v16, v3
	v_cndmask_b32_e64 v3, v19, 0, s[42:43]
	v_add_f32_e32 v3, v3, v7
	v_cndmask_b32_e64 v7, 0, v135, s[46:47]
	v_add_f32_e32 v131, v3, v7
	v_pk_add_f32 v[128:129], v[128:129], v[130:131]
	v_mov_b32_e32 v134, v8
	v_sub_f32_e32 v3, v128, v129
	v_mul_f32_e32 v3, 0x3fb8aa3b, v3
	v_exp_f32_e32 v17, v3
	s_nop 0
	v_pk_mul_f32 v[14:15], v[14:15], v[16:17]
	s_nop 0
	v_cvt_pk_bf16_f32 v3, v14, s0
	ds_write_b16 v119, v3 offset:36384
	v_sub_f32_e32 v3, v129, v128
	v_mul_f32_e32 v3, 0x3fb8aa3b, v3
	v_exp_f32_e32 v19, v3
	v_cvt_pk_bf16_f32 v3, v15, s0
	ds_write_b16 v119, v3 offset:36528
	v_cvt_pk_bf16_f32 v3, v14, v15
	v_pk_mul_f32 v[12:13], v[18:19], v[12:13]
	v_cndmask_b32_e64 v128, v8, 0, s[42:43]
	v_cvt_pk_bf16_f32 v7, v12, v13
	ds_read_b128 v[12:15], v112 offset:16912
	ds_read_b128 v[16:19], v112 offset:17168
	ds_read2_b32 v[130:131], v100 offset0:4 offset1:5
	s_waitcnt lgkmcnt(2)
	v_cndmask_b32_e64 v12, 0, v12, s[44:45]
	v_add_f32_e32 v12, v128, v12
	s_waitcnt lgkmcnt(1)
	v_cndmask_b32_e64 v16, 0, v16, s[46:47]
	v_add_f32_e32 v129, v12, v16
	v_add_u32_e32 v12, 0x1f8c, v112
	ds_read2_b32 v[132:133], v12 offset1:1
	v_cndmask_b32_e64 v16, v9, 0, s[42:43]
	v_cndmask_b32_e64 v13, 0, v13, s[44:45]
	v_add_f32_e32 v13, v16, v13
	v_cndmask_b32_e64 v16, 0, v17, s[46:47]
	s_waitcnt lgkmcnt(1)
	v_mov_b32_e32 v135, v130
	s_waitcnt lgkmcnt(0)
; DI u16 f2bf(float x) { return (u16)pack2(x, 0.f); }
; DI void hgrn_unit(const P& p, int l, int unit, char* lds_all) {
;     ...
;     {
;       const int sg = tau >> 4;
;       unsigned qmw[8], kmw[8];
; #pragma unroll
;       for (int e = 0; e < 8; ++e) {
;         float qq[2], km2[2];
; #pragma unroll
;         for (int u = 0; u < 2; ++u) {
;           const int i = 2 * e + u, k = kc + i;
;           const float s0 = Seg[k], s1 = Seg[64 + k], s2 = Seg[128 + k];
;           const float off = (sg > 0 ? s0 : 0.f) + (sg > 1 ? s1 : 0.f) + (sg > 2 ? s2 : 0.f);
;           const float bc = Lf[tau * 65 + k] + off;
;           const float rr = Lf[31 * 65 + k] + s0;
;           qq[u] = qv[i] * __expf(bc - rr);
;           km2[u] = kk[i] * __expf(rr - bc);
;           KmT[k * 72 + tau] = f2bf(km2[u]);
;         }
;         qmw[e] = pack2(qq[0], qq[1]);
;         kmw[e] = pack2(km2[0], km2[1]);
;       }
;       *(uint4*)&Qm[tau * 72 + kc] = make_uint4(qmw[0], qmw[1], qmw[2], qmw[3]);
;       *(uint4*)&Qm[tau * 72 + kc + 8] = make_uint4(qmw[4], qmw[5], qmw[6], qmw[7]);
;       *(uint4*)&Km[tau * 72 + kc] = make_uint4(kmw[0], kmw[1], kmw[2], kmw[3]);
;       *(uint4*)&Km[tau * 72 + kc + 8] = make_uint4(kmw[4], kmw[5], kmw[6], kmw[7]);
	v_mov_b32_e32 v128, v132
	v_add_f32_e32 v17, v13, v16
	v_mov_b32_e32 v130, v9
	v_mov_b32_e32 v16, v133
	v_pk_add_f32 v[128:129], v[134:135], v[128:129]
	v_pk_add_f32 v[16:17], v[130:131], v[16:17]
	v_sub_f32_e32 v12, v128, v129
	v_sub_f32_e32 v9, v16, v17
	v_mul_f32_e32 v12, 0x3fb8aa3b, v12
	v_mul_f32_e32 v9, 0x3fb8aa3b, v9
	v_exp_f32_e32 v12, v12
	v_exp_f32_e32 v13, v9
	v_sub_f32_e32 v8, v129, v128
	v_mul_f32_e32 v8, 0x3fb8aa3b, v8
	v_exp_f32_e32 v8, v8
	v_pk_mul_f32 v[4:5], v[4:5], v[12:13]
	v_mov_b32_e32 v128, v10
	v_cvt_pk_bf16_f32 v9, v4, s0
	ds_write_b16 v119, v9 offset:36672
	v_sub_f32_e32 v9, v17, v16
	v_mul_f32_e32 v9, 0x3fb8aa3b, v9
	v_exp_f32_e32 v9, v9
	v_cvt_pk_bf16_f32 v12, v5, s0
	v_cvt_pk_bf16_f32 v4, v4, v5
	v_cndmask_b32_e64 v5, v10, 0, s[42:43]
	v_pk_mul_f32 v[8:9], v[8:9], v[26:27]
	ds_read2_b32 v[16:17], v100 offset0:6 offset1:7
	v_cvt_pk_bf16_f32 v8, v8, v9
	v_cndmask_b32_e64 v9, 0, v14, s[44:45]
	v_add_f32_e32 v5, v5, v9
	v_cndmask_b32_e64 v9, 0, v18, s[46:47]
	v_add_f32_e32 v13, v5, v9
	v_add_u32_e32 v5, 0x1f94, v112
	ds_read2_b32 v[26:27], v5 offset1:1
	ds_write_b16 v119, v12 offset:36816
	s_waitcnt lgkmcnt(2)
	v_mov_b32_e32 v129, v16
	v_cndmask_b32_e64 v9, 0, v15, s[44:45]
	v_mov_b32_e32 v16, v11
	s_waitcnt lgkmcnt(1)
	v_mov_b32_e32 v12, v26
	v_pk_add_f32 v[12:13], v[128:129], v[12:13]
	v_mov_b32_e32 v14, v27
	v_sub_f32_e32 v5, v13, v12
	v_mul_f32_e32 v5, 0x3fb8aa3b, v5
	v_exp_f32_e32 v10, v5
	v_sub_f32_e32 v5, v12, v13
	v_mul_f32_e32 v5, 0x3fb8aa3b, v5
	v_exp_f32_e32 v12, v5
	v_cndmask_b32_e64 v5, v11, 0, s[42:43]
	v_add_f32_e32 v5, v5, v9
	v_cndmask_b32_e64 v9, 0, v19, s[46:47]
	v_add_f32_e32 v15, v5, v9
	v_pk_add_f32 v[14:15], v[16:17], v[14:15]
	s_nop 0
	v_sub_f32_e32 v5, v14, v15
	v_mul_f32_e32 v5, 0x3fb8aa3b, v5
	v_exp_f32_e32 v13, v5
	s_nop 0
	v_pk_mul_f32 v[12:13], v[90:91], v[12:13]
	s_nop 0
	v_cvt_pk_bf16_f32 v5, v12, s0
	ds_write_b16 v119, v5 offset:36960
	v_sub_f32_e32 v5, v15, v14
	v_mul_f32_e32 v5, 0x3fb8aa3b, v5
	v_exp_f32_e32 v11, v5
	v_cvt_pk_bf16_f32 v5, v13, s0
	ds_write_b16 v119, v5 offset:37104
	v_cvt_pk_bf16_f32 v5, v12, v13
	v_pk_mul_f32 v[10:11], v[10:11], v[24:25]
	s_nop 0
	v_cvt_pk_bf16_f32 v9, v10, v11
	ds_read_b128 v[10:13], v112 offset:16672
	ds_read_b128 v[16:19], v112 offset:16688
	ds_read_b128 v[24:27], v112 offset:16928
	ds_read_b128 v[128:131], v112 offset:17184
	ds_read2_b32 v[90:91], v100 offset0:8 offset1:9
	s_waitcnt lgkmcnt(4)
	v_cndmask_b32_e64 v14, v10, 0, s[42:43]
	v_mov_b32_e32 v134, v10
	s_waitcnt lgkmcnt(2)
	v_cndmask_b32_e64 v15, 0, v24, s[44:45]
	v_add_f32_e32 v14, v14, v15
	s_waitcnt lgkmcnt(1)
	v_cndmask_b32_e64 v15, 0, v128, s[46:47]
	v_add_f32_e32 v15, v14, v15
	v_add_u32_e32 v14, 0x1f9c, v112
	ds_read2_b32 v[132:133], v14 offset1:1
	s_waitcnt lgkmcnt(1)
	v_mov_b32_e32 v135, v90
	v_cndmask_b32_e64 v24, 0, v25, s[44:45]
	v_mov_b32_e32 v90, v11
	s_waitcnt lgkmcnt(0)
	v_mov_b32_e32 v14, v132
	v_pk_add_f32 v[14:15], v[134:135], v[14:15]
	s_nop 0
	v_sub_f32_e32 v10, v15, v14
	v_sub_f32_e32 v14, v14, v15
	v_cndmask_b32_e64 v15, v11, 0, s[42:43]
	v_add_f32_e32 v15, v15, v24
	v_cndmask_b32_e64 v24, 0, v129, s[46:47]
	v_add_f32_e32 v25, v15, v24
	v_mov_b32_e32 v24, v133
	v_pk_add_f32 v[24:25], v[90:91], v[24:25]
	v_mul_f32_e32 v14, 0x3fb8aa3b, v14
	v_sub_f32_e32 v11, v24, v25
	v_mul_f32_e32 v11, 0x3fb8aa3b, v11
	v_exp_f32_e32 v14, v14
	v_exp_f32_e32 v15, v11
	v_mul_f32_e32 v10, 0x3fb8aa3b, v10
	v_exp_f32_e32 v10, v10
	v_pk_mul_f32 v[90:91], v[94:95], v[14:15]
	s_nop 0
	v_cvt_pk_bf16_f32 v11, v90, s0
	ds_write_b16 v119, v11 offset:37248
	v_sub_f32_e32 v11, v25, v24
	v_mul_f32_e32 v11, 0x3fb8aa3b, v11
	v_exp_f32_e32 v11, v11
	v_cvt_pk_bf16_f32 v14, v91, s0
	ds_write_b16 v119, v14 offset:37392
	v_cndmask_b32_e64 v15, 0, v26, s[44:45]
	v_pk_mul_f32 v[10:11], v[10:11], v[22:23]
	ds_read2_b32 v[24:25], v100 offset0:10 offset1:11
	v_cvt_pk_bf16_f32 v14, v10, v11
	v_cndmask_b32_e64 v11, v12, 0, s[42:43]
	v_add_f32_e32 v11, v11, v15
	v_cndmask_b32_e64 v15, 0, v130, s[46:47]
	v_add_f32_e32 v23, v11, v15
	v_add_u32_e32 v11, 0x1fa4, v112
	v_cvt_pk_bf16_f32 v10, v90, v91
	ds_read2_b32 v[90:91], v11 offset1:1
	v_mov_b32_e32 v94, v12
	s_waitcnt lgkmcnt(1)
	v_mov_b32_e32 v95, v24
	v_cndmask_b32_e64 v15, 0, v27, s[44:45]
	v_mov_b32_e32 v24, v13
	s_waitcnt lgkmcnt(0)
	v_mov_b32_e32 v22, v90
	v_pk_add_f32 v[22:23], v[94:95], v[22:23]
	v_mov_b32_e32 v26, v91
	v_sub_f32_e32 v11, v23, v22
	v_mul_f32_e32 v11, 0x3fb8aa3b, v11
	v_exp_f32_e32 v12, v11
	v_sub_f32_e32 v11, v22, v23
	v_mul_f32_e32 v11, 0x3fb8aa3b, v11
	v_exp_f32_e32 v22, v11
	v_cndmask_b32_e64 v11, v13, 0, s[42:43]
	v_add_f32_e32 v11, v11, v15
	v_cndmask_b32_e64 v15, 0, v131, s[46:47]
	v_add_f32_e32 v27, v11, v15
	v_pk_add_f32 v[24:25], v[24:25], v[26:27]
	s_nop 0
	v_sub_f32_e32 v11, v24, v25
	v_mul_f32_e32 v11, 0x3fb8aa3b, v11
	v_exp_f32_e32 v23, v11
	s_nop 0
	v_pk_mul_f32 v[22:23], v[96:97], v[22:23]
	s_nop 0
	v_cvt_pk_bf16_f32 v11, v22, s0
	ds_write_b16 v119, v11 offset:37536
	v_sub_f32_e32 v11, v25, v24
	v_mul_f32_e32 v11, 0x3fb8aa3b, v11
	v_exp_f32_e32 v13, v11
	v_cvt_pk_bf16_f32 v11, v23, s0
	ds_write_b16 v119, v11 offset:37680
	v_cvt_pk_bf16_f32 v11, v22, v23
	v_pk_mul_f32 v[12:13], v[12:13], v[20:21]
	ds_read_b128 v[20:23], v112 offset:16944
	ds_read_b128 v[24:27], v112 offset:17200
	v_cvt_pk_bf16_f32 v15, v12, v13
	v_cndmask_b32_e64 v12, v16, 0, s[42:43]
	ds_read2_b32 v[90:91], v100 offset0:12 offset1:13
	s_waitcnt lgkmcnt(2)
	v_cndmask_b32_e64 v13, 0, v20, s[44:45]
	v_add_f32_e32 v12, v12, v13
	s_waitcnt lgkmcnt(1)
	v_cndmask_b32_e64 v13, 0, v24, s[46:47]
	v_add_f32_e32 v13, v12, v13
	v_add_u32_e32 v12, 0x1fac, v112
	ds_read2_b32 v[94:95], v12 offset1:1
	v_mov_b32_e32 v96, v16
	s_waitcnt lgkmcnt(1)
; DI u16 f2bf(float x) { return (u16)pack2(x, 0.f); }
; DI void hgrn_unit(const P& p, int l, int unit, char* lds_all) {
;     ...
;     {
;       const int sg = tau >> 4;
;       unsigned qmw[8], kmw[8];
; #pragma unroll
;       for (int e = 0; e < 8; ++e) {
;         float qq[2], km2[2];
; #pragma unroll
;         for (int u = 0; u < 2; ++u) {
;           const int i = 2 * e + u, k = kc + i;
;           const float s0 = Seg[k], s1 = Seg[64 + k], s2 = Seg[128 + k];
;           const float off = (sg > 0 ? s0 : 0.f) + (sg > 1 ? s1 : 0.f) + (sg > 2 ? s2 : 0.f);
;           const float bc = Lf[tau * 65 + k] + off;
;           const float rr = Lf[31 * 65 + k] + s0;
;           qq[u] = qv[i] * __expf(bc - rr);
;           km2[u] = kk[i] * __expf(rr - bc);
;           KmT[k * 72 + tau] = f2bf(km2[u]);
;         }
;         qmw[e] = pack2(qq[0], qq[1]);
;         kmw[e] = pack2(km2[0], km2[1]);
;       }
;       *(uint4*)&Qm[tau * 72 + kc] = make_uint4(qmw[0], qmw[1], qmw[2], qmw[3]);
;       *(uint4*)&Qm[tau * 72 + kc + 8] = make_uint4(qmw[4], qmw[5], qmw[6], qmw[7]);
;       *(uint4*)&Km[tau * 72 + kc] = make_uint4(kmw[0], kmw[1], kmw[2], kmw[3]);
;       *(uint4*)&Km[tau * 72 + kc + 8] = make_uint4(kmw[4], kmw[5], kmw[6], kmw[7]);
; #pragma unroll
;       for (int nt = 0; nt < 4; ++nt) {
;         const int k = nt * 16 + r;
;         const float er = __expf(Lf[31 * 65 + k] + Seg[k]);
; #pragma unroll
;         for (int j = 0; j < 4; ++j) St[(w * 16 + g * 4 + j) * 72 + k] = f2bf(Sacc[nt][j] * er);
;       }
;     }
;     __syncthreads();
	v_mov_b32_e32 v97, v90
	v_cndmask_b32_e64 v20, 0, v21, s[44:45]
	v_mov_b32_e32 v90, v17
	s_waitcnt lgkmcnt(0)
	v_mov_b32_e32 v12, v94
	v_pk_add_f32 v[12:13], v[96:97], v[12:13]
	v_add_u32_e32 v96, v127, v115
	v_sub_f32_e32 v16, v13, v12
	v_sub_f32_e32 v12, v12, v13
	v_cndmask_b32_e64 v13, v17, 0, s[42:43]
	v_add_f32_e32 v13, v13, v20
	v_cndmask_b32_e64 v20, 0, v25, s[46:47]
	v_add_f32_e32 v21, v13, v20
	v_mov_b32_e32 v20, v95
	v_pk_add_f32 v[20:21], v[90:91], v[20:21]
	v_mul_f32_e32 v12, 0x3fb8aa3b, v12
	v_sub_f32_e32 v13, v20, v21
	v_mul_f32_e32 v13, 0x3fb8aa3b, v13
	v_exp_f32_e32 v12, v12
	v_exp_f32_e32 v13, v13
	v_mul_f32_e32 v16, 0x3fb8aa3b, v16
	v_exp_f32_e32 v16, v16
	ds_read2_b32 v[24:25], v100 offset0:14 offset1:15
	v_pk_mul_f32 v[12:13], v[92:93], v[12:13]
	v_mov_b32_e32 v90, v18
	v_cvt_pk_bf16_f32 v17, v12, s0
	ds_write_b16 v119, v17 offset:37824
	v_sub_f32_e32 v17, v21, v20
	v_mul_f32_e32 v17, 0x3fb8aa3b, v17
	v_exp_f32_e32 v17, v17
	v_cvt_pk_bf16_f32 v20, v13, s0
	v_cvt_pk_bf16_f32 v12, v12, v13
	v_cndmask_b32_e64 v13, v18, 0, s[42:43]
	v_pk_mul_f32 v[16:17], v[16:17], v[86:87]
	ds_write_b16 v119, v20 offset:37968
	v_cvt_pk_bf16_f32 v16, v16, v17
	v_cndmask_b32_e64 v17, 0, v22, s[44:45]
	v_add_f32_e32 v13, v13, v17
	v_cndmask_b32_e64 v17, 0, v26, s[46:47]
	v_add_f32_e32 v21, v13, v17
	v_add_u32_e32 v13, 0x1fb4, v112
	ds_read2_b32 v[86:87], v13 offset1:1
	s_waitcnt lgkmcnt(3)
	v_mov_b32_e32 v91, v24
	v_cndmask_b32_e64 v17, 0, v23, s[44:45]
	v_mov_b32_e32 v24, v19
	v_add_u32_e32 v26, v127, v114
	s_waitcnt lgkmcnt(0)
	v_mov_b32_e32 v20, v86
	v_pk_add_f32 v[20:21], v[90:91], v[20:21]
	v_mov_b32_e32 v22, v87
	v_sub_f32_e32 v13, v21, v20
	v_mul_f32_e32 v13, 0x3fb8aa3b, v13
	v_exp_f32_e32 v18, v13
	v_sub_f32_e32 v13, v20, v21
	v_mul_f32_e32 v13, 0x3fb8aa3b, v13
	v_exp_f32_e32 v20, v13
	v_cndmask_b32_e64 v13, v19, 0, s[42:43]
	v_add_f32_e32 v13, v13, v17
	v_cndmask_b32_e64 v17, 0, v27, s[46:47]
	v_add_f32_e32 v23, v13, v17
	v_pk_add_f32 v[22:23], v[24:25], v[22:23]
	v_ashrrev_i32_e32 v27, 31, v26
	v_sub_f32_e32 v13, v22, v23
	v_mul_f32_e32 v13, 0x3fb8aa3b, v13
	v_exp_f32_e32 v21, v13
	v_lshlrev_b64 v[26:27], 8, v[26:27]
	v_ashrrev_i32_e32 v97, 31, v96
	v_lshl_add_u64 v[26:27], v[50:51], 0, v[26:27]
	v_pk_mul_f32 v[20:21], v[88:89], v[20:21]
	v_lshlrev_b64 v[96:97], 8, v[96:97]
	v_cvt_pk_bf16_f32 v13, v20, s0
	ds_write_b16 v119, v13 offset:38112
	v_sub_f32_e32 v13, v23, v22
	v_mul_f32_e32 v13, 0x3fb8aa3b, v13
	v_exp_f32_e32 v19, v13
	v_cvt_pk_bf16_f32 v13, v21, s0
	ds_write_b16 v119, v13 offset:38256
	v_cvt_pk_bf16_f32 v13, v20, v21
	v_pk_mul_f32 v[18:19], v[18:19], v[84:85]
	v_lshl_add_u64 v[96:97], v[50:51], 0, v[96:97]
	v_cvt_pk_bf16_f32 v17, v18, v19
	ds_write_b128 v102, v[6:9] offset:17664
	ds_write_b128 v102, v[14:17] offset:17680
	ds_write_b128 v102, v[2:5] offset:26880
	ds_write_b128 v102, v[10:13] offset:26896
	v_add_u32_e32 v12, 0x1c00, v0
	v_add_u32_e32 v10, 0x4000, v0
	ds_read2_b32 v[2:3], v12 offset0:223 offset1:239
	ds_read2_b32 v[4:5], v10 offset0:64 offset1:80
	v_add_u32_e32 v11, 0x1e00, v0
	s_waitcnt lgkmcnt(0)
	v_add_f32_e32 v2, v2, v4
	v_mul_f32_e32 v2, 0x3fb8aa3b, v2
	v_exp_f32_e32 v2, v2
	s_nop 0
	v_mul_f32_e32 v4, v68, v2
	v_cvt_pk_bf16_f32 v4, v4, s0
	ds_write_b16 v120, v4 offset:63744
	v_mul_f32_e32 v4, v69, v2
	v_cvt_pk_bf16_f32 v4, v4, s0
	ds_write_b16 v120, v4 offset:63888
	v_mul_f32_e32 v4, v70, v2
	v_mul_f32_e32 v2, v71, v2
	v_cvt_pk_bf16_f32 v2, v2, s0
	ds_write_b16 v120, v2 offset:64176
	v_add_f32_e32 v2, v3, v5
	v_mul_f32_e32 v2, 0x3fb8aa3b, v2
	v_exp_f32_e32 v2, v2
	v_cvt_pk_bf16_f32 v4, v4, s0
	ds_write_b16 v120, v4 offset:64032
	v_mul_f32_e32 v3, v72, v2
	v_cvt_pk_bf16_f32 v3, v3, s0
	ds_write_b16 v120, v3 offset:63776
	v_mul_f32_e32 v3, v73, v2
	v_cvt_pk_bf16_f32 v3, v3, s0
	ds_write_b16 v120, v3 offset:63920
	v_mul_f32_e32 v3, v74, v2
	v_mul_f32_e32 v2, v75, v2
	v_cvt_pk_bf16_f32 v3, v3, s0
	v_cvt_pk_bf16_f32 v2, v2, s0
	ds_write_b16 v120, v3 offset:64064
	ds_write_b16 v120, v2 offset:64208
	ds_read2_b32 v[2:3], v11 offset0:127 offset1:143
	ds_read2_b32 v[4:5], v10 offset0:96 offset1:112
	s_waitcnt lgkmcnt(0)
	v_add_f32_e32 v2, v2, v4
	v_mul_f32_e32 v2, 0x3fb8aa3b, v2
	v_exp_f32_e32 v2, v2
	s_nop 0
	v_mul_f32_e32 v4, v76, v2
	v_cvt_pk_bf16_f32 v4, v4, s0
	ds_write_b16 v120, v4 offset:63808
	v_mul_f32_e32 v4, v77, v2
	v_cvt_pk_bf16_f32 v4, v4, s0
	ds_write_b16 v120, v4 offset:63952
	v_mul_f32_e32 v4, v78, v2
	v_mul_f32_e32 v2, v79, v2
	v_cvt_pk_bf16_f32 v2, v2, s0
	ds_write_b16 v120, v2 offset:64240
	v_add_f32_e32 v2, v3, v5
	v_mul_f32_e32 v2, 0x3fb8aa3b, v2
	v_exp_f32_e32 v2, v2
	v_cvt_pk_bf16_f32 v4, v4, s0
	ds_write_b16 v120, v4 offset:64096
	v_mul_f32_e32 v3, v80, v2
	v_cvt_pk_bf16_f32 v3, v3, s0
	ds_write_b16 v120, v3 offset:63840
	v_mul_f32_e32 v3, v81, v2
	v_cvt_pk_bf16_f32 v3, v3, s0
	ds_write_b16 v120, v3 offset:63984
	v_mul_f32_e32 v3, v82, v2
	v_mul_f32_e32 v2, v83, v2
	v_cvt_pk_bf16_f32 v3, v3, s0
	v_cvt_pk_bf16_f32 v2, v2, s0
	ds_write_b16 v120, v3 offset:64128
	ds_write_b16 v120, v2 offset:64272
	s_waitcnt lgkmcnt(0)
	s_barrier
; #define MFMA(a, b, c) __builtin_amdgcn_mfma_f32_16x16x32_bf16((a), (b), (c), 0, 0, 0)
; DI u16 f2bf(float x) { return (u16)pack2(x, 0.f); }
; DI void hgrn_unit(const P& p, int l, int unit, char* lds_all) {
;     ...
;     bf16x8 aq[2];
; #pragma unroll
;     for (int ks = 0; ks < 2; ++ks) aq[ks] = *(const bf16x8*)&Qm[(w * 16 + r) * 72 + ks * 32 + g * 8];
;     f32x4 oacc[4];
; #pragma unroll
;     for (int nt = 0; nt < 4; ++nt) {
;       f32x4 a = zero4();
; #pragma unroll
;       for (int ks = 0; ks < 2; ++ks) {
;         const bf16x8 bk = *(const bf16x8*)&Km[(nt * 16 + r) * 72 + ks * 32 + g * 8];
;         a = MFMA(aq[ks], bk, a);
;       }
; #pragma unroll
;       for (int j = 0; j < 4; ++j) {
;         const bool keep = (nt * 16 + r) <= (w * 16 + g * 4 + j);
;         const float v = keep ? a[j] : 0.f;
;         Att[(w * 16 + g * 4 + j) * 72 + nt * 16 + r] = f2bf(v);
;       }
;     }
; #pragma unroll
;     for (int nt = 0; nt < 4; ++nt) {
;       f32x4 a = zero4();
; #pragma unroll
;       for (int ks = 0; ks < 2; ++ks) {
;         const bf16x8 bs = *(const bf16x8*)&St[(nt * 16 + r) * 72 + ks * 32 + g * 8];
;         a = MFMA(aq[ks], bs, a);
;       }
;       oacc[nt] = a;
;     }
;     __syncthreads();
	ds_read_b128 v[2:5], v121 offset:17664
	ds_read_b128 v[6:9], v121 offset:17728
	ds_read_b128 v[14:17], v122 offset:26880
	ds_read_b128 v[18:21], v122 offset:26944
	s_waitcnt lgkmcnt(1)
	v_mfma_f32_16x16x32_bf16 v[14:17], v[2:5], v[14:17], 0
	s_waitcnt lgkmcnt(0)
	v_mfma_f32_16x16x32_bf16 v[14:17], v[6:9], v[18:21], v[14:17]
	s_nop 7
	v_cvt_pk_bf16_f32 v13, v14, s0
	v_cndmask_b32_e64 v13, v13, 0, s[48:49]
	ds_write_b16 v123, v13 offset:54528
	v_cvt_pk_bf16_f32 v13, v15, s0
	v_cndmask_b32_e64 v13, v13, 0, s[50:51]
	ds_write_b16 v123, v13 offset:54672
	v_cvt_pk_bf16_f32 v13, v16, s0
	v_cndmask_b32_e64 v13, v13, 0, s[52:53]
	ds_write_b16 v123, v13 offset:54816
	v_cvt_pk_bf16_f32 v13, v17, s0
	v_cndmask_b32_e64 v13, v13, 0, s[54:55]
	ds_write_b16 v123, v13 offset:54960
	ds_read_b128 v[14:17], v122 offset:29184
	ds_read_b128 v[18:21], v122 offset:29248
	s_waitcnt lgkmcnt(1)
	v_mfma_f32_16x16x32_bf16 v[14:17], v[2:5], v[14:17], 0
	s_waitcnt lgkmcnt(0)
	v_mfma_f32_16x16x32_bf16 v[14:17], v[6:9], v[18:21], v[14:17]
	s_nop 7
	v_cvt_pk_bf16_f32 v13, v14, s0
	v_cndmask_b32_e64 v13, v13, 0, s[56:57]
	ds_write_b16 v123, v13 offset:54560
	v_cvt_pk_bf16_f32 v13, v15, s0
	v_cndmask_b32_e64 v13, v13, 0, s[58:59]
	ds_write_b16 v123, v13 offset:54704
	v_cvt_pk_bf16_f32 v13, v16, s0
	v_cndmask_b32_e64 v13, v13, 0, s[60:61]
	ds_write_b16 v123, v13 offset:54848
	v_cvt_pk_bf16_f32 v13, v17, s0
	v_cndmask_b32_e64 v13, v13, 0, s[62:63]
	ds_write_b16 v123, v13 offset:54992
	ds_read_b128 v[14:17], v122 offset:31488
	ds_read_b128 v[18:21], v122 offset:31552
	s_waitcnt lgkmcnt(1)
	v_mfma_f32_16x16x32_bf16 v[14:17], v[2:5], v[14:17], 0
	s_waitcnt lgkmcnt(0)
	v_mfma_f32_16x16x32_bf16 v[14:17], v[6:9], v[18:21], v[14:17]
	s_nop 7
	v_cvt_pk_bf16_f32 v13, v14, s0
	v_cndmask_b32_e64 v13, v13, 0, s[64:65]
	ds_write_b16 v123, v13 offset:54592
	v_cvt_pk_bf16_f32 v13, v15, s0
	v_cndmask_b32_e64 v13, v13, 0, s[66:67]
	ds_write_b16 v123, v13 offset:54736
	v_cvt_pk_bf16_f32 v13, v16, s0
	v_cndmask_b32_e64 v13, v13, 0, s[68:69]
	ds_write_b16 v123, v13 offset:54880
	v_cvt_pk_bf16_f32 v13, v17, s0
	v_cndmask_b32_e64 v13, v13, 0, s[70:71]
	ds_write_b16 v123, v13 offset:55024
	ds_read_b128 v[14:17], v122 offset:33792
	ds_read_b128 v[18:21], v122 offset:33856
	s_waitcnt lgkmcnt(1)
	v_mfma_f32_16x16x32_bf16 v[14:17], v[2:5], v[14:17], 0
	s_waitcnt lgkmcnt(0)
	v_mfma_f32_16x16x32_bf16 v[14:17], v[6:9], v[18:21], v[14:17]
	s_nop 7
	v_cvt_pk_bf16_f32 v13, v14, s0
	v_cndmask_b32_e64 v13, v13, 0, s[72:73]
	ds_write_b16 v123, v13 offset:54624
	v_cvt_pk_bf16_f32 v13, v15, s0
	v_cndmask_b32_e64 v13, v13, 0, s[74:75]
	ds_write_b16 v123, v13 offset:54768
	v_cvt_pk_bf16_f32 v13, v16, s0
	v_cndmask_b32_e64 v13, v13, 0, s[76:77]
	ds_write_b16 v123, v13 offset:54912
	v_cvt_pk_bf16_f32 v13, v17, s0
	v_cndmask_b32_e64 v13, v13, 0, s[78:79]
	ds_write_b16 v123, v13 offset:55056
	ds_read_b128 v[14:17], v122 offset:63744
	ds_read_b128 v[18:21], v122 offset:63808
	s_waitcnt lgkmcnt(1)
	v_mfma_f32_16x16x32_bf16 v[14:17], v[2:5], v[14:17], 0
	ds_read_b128 v[22:25], v124 offset:63808
	ds_read_b128 v[84:87], v125 offset:63808
	s_waitcnt lgkmcnt(2)
	v_mfma_f32_16x16x32_bf16 v[14:17], v[6:9], v[18:21], v[14:17]
	ds_read_b128 v[18:21], v124 offset:63744
	s_waitcnt lgkmcnt(0)
	v_mfma_f32_16x16x32_bf16 v[18:21], v[2:5], v[18:21], 0
	v_mfma_f32_16x16x32_bf16 v[18:21], v[6:9], v[22:25], v[18:21]
	ds_read_b128 v[22:25], v125 offset:63744
	s_waitcnt lgkmcnt(0)
	v_mfma_f32_16x16x32_bf16 v[22:25], v[2:5], v[22:25], 0
	v_mfma_f32_16x16x32_bf16 v[22:25], v[6:9], v[84:87], v[22:25]
	ds_read_b128 v[84:87], v126 offset:63744
	s_waitcnt lgkmcnt(0)
	v_mfma_f32_16x16x32_bf16 v[2:5], v[2:5], v[84:87], 0
	ds_read_b128 v[84:87], v126 offset:63808
	s_waitcnt lgkmcnt(0)
	s_barrier
; #define MFMA(a, b, c) __builtin_amdgcn_mfma_f32_16x16x32_bf16((a), (b), (c), 0, 0, 0)
; DI void hgrn_unit(const P& p, int l, int unit, char* lds_all) {
;     ...
;     bf16x8 aa[2], av[2];
; #pragma unroll
;     for (int ks = 0; ks < 2; ++ks) {
;       aa[ks] = *(const bf16x8*)&Att[(w * 16 + r) * 72 + ks * 32 + g * 8];
;       av[ks] = *(const bf16x8*)&Vt[(w * 16 + r) * 72 + ks * 32 + g * 8];
;     }
; #pragma unroll
;     for (int nt = 0; nt < 4; ++nt) {
; #pragma unroll
;       for (int ks = 0; ks < 2; ++ks) {
;         const bf16x8 bv = *(const bf16x8*)&Vt[(nt * 16 + r) * 72 + ks * 32 + g * 8];
;         oacc[nt] = MFMA(aa[ks], bv, oacc[nt]);
;       }
; #pragma unroll
;       for (int j = 0; j < 4; ++j) {
;         const int t = w * 16 + g * 4 + j;
;         const int tk = base + (dir ? 63 - t : t);
;         Og[(size_t)tk * 64 + nt * 16 + r] = oacc[nt][j];
;       }
;     }
; #pragma unroll
;     for (int nt = 0; nt < 4; ++nt) {
;       f32x4 u = zero4();
; #pragma unroll
;       for (int ks = 0; ks < 2; ++ks) {
;         const bf16x8 bk = *(const bf16x8*)&KmT[(nt * 16 + r) * 72 + ks * 32 + g * 8];
;         u = MFMA(av[ks], bk, u);
;       }
;       const int k = nt * 16 + r;
;       const float s0 = Seg[k], s1 = Seg[64 + k], s2 = Seg[128 + k], s3 = Seg[192 + k];
;       const float blast = s0 + s1 + s2 + s3;
;       const float rk = Lf[31 * 65 + k] + s0;
;       const float e1 = __expf(blast), e2 = __expf(blast - rk);
; #pragma unroll
;       for (int j = 0; j < 4; ++j) Sacc[nt][j] = e1 * Sacc[nt][j] + e2 * u[j];
;     }
;     __syncthreads();
	v_mfma_f32_16x16x32_bf16 v[84:87], v[6:9], v[84:87], v[2:5]
	ds_read_b128 v[88:91], v113 offset:54528
	ds_read_b128 v[6:9], v113 offset:45312
	ds_read_b128 v[92:95], v113 offset:54592
	s_nop 0
	ds_read_b128 v[2:5], v113 offset:45376
	ds_read_b128 v[128:131], v122 offset:45312
	s_waitcnt lgkmcnt(0)
	v_mfma_f32_16x16x32_bf16 v[14:17], v[88:91], v[128:131], v[14:17]
	ds_read_b128 v[128:131], v122 offset:45376
	s_waitcnt lgkmcnt(0)
	v_mfma_f32_16x16x32_bf16 v[14:17], v[92:95], v[128:131], v[14:17]
	s_nop 7
	global_store_dword v[26:27], v14, off
	v_add_u32_e32 v14, v127, v116
	global_store_dword v[96:97], v15, off
	v_ashrrev_i32_e32 v15, 31, v14
	v_lshlrev_b64 v[14:15], 8, v[14:15]
	v_lshl_add_u64 v[128:129], v[50:51], 0, v[14:15]
	v_add_u32_e32 v14, v127, v117
	v_ashrrev_i32_e32 v15, 31, v14
	v_lshlrev_b64 v[14:15], 8, v[14:15]
	v_lshl_add_u64 v[130:131], v[50:51], 0, v[14:15]
	global_store_dword v[128:129], v16, off
	global_store_dword v[130:131], v17, off
	ds_read_b128 v[14:17], v122 offset:47616
	s_waitcnt lgkmcnt(0)
	v_mfma_f32_16x16x32_bf16 v[14:17], v[88:91], v[14:17], v[18:21]
	s_nop 2
	ds_read_b128 v[18:21], v122 offset:47680
	s_waitcnt lgkmcnt(0)
	v_mfma_f32_16x16x32_bf16 v[14:17], v[92:95], v[18:21], v[14:17]
	s_nop 7
	global_store_dword v[26:27], v14, off offset:64
	global_store_dword v[96:97], v15, off offset:64
	global_store_dword v[128:129], v16, off offset:64
	global_store_dword v[130:131], v17, off offset:64
	ds_read_b128 v[14:17], v122 offset:49920
	ds_read_b128 v[18:21], v122 offset:49984
	s_waitcnt lgkmcnt(1)
	v_mfma_f32_16x16x32_bf16 v[14:17], v[88:91], v[14:17], v[22:25]
	s_waitcnt lgkmcnt(0)
	v_mfma_f32_16x16x32_bf16 v[14:17], v[92:95], v[18:21], v[14:17]
	s_nop 7
	global_store_dword v[26:27], v14, off offset:128
	global_store_dword v[96:97], v15, off offset:128
	global_store_dword v[128:129], v16, off offset:128
	global_store_dword v[130:131], v17, off offset:128
	ds_read_b128 v[14:17], v122 offset:52224
	ds_read_b128 v[18:21], v122 offset:52288
	s_waitcnt lgkmcnt(1)
	v_mfma_f32_16x16x32_bf16 v[14:17], v[88:91], v[14:17], v[84:87]
	s_nop 2
	v_add_u32_e32 v86, 0x4400, v0
	s_waitcnt lgkmcnt(0)
	v_mfma_f32_16x16x32_bf16 v[14:17], v[92:95], v[18:21], v[14:17]
	s_nop 7
	global_store_dword v[26:27], v14, off offset:192
	global_store_dword v[96:97], v15, off offset:192
	global_store_dword v[128:129], v16, off offset:192
	global_store_dword v[130:131], v17, off offset:192
	ds_read_b128 v[14:17], v122 offset:36096
	ds_read_b128 v[18:21], v122 offset:36160
	s_waitcnt lgkmcnt(1)
	v_mfma_f32_16x16x32_bf16 v[14:17], v[6:9], v[14:17], 0
	s_waitcnt lgkmcnt(0)
	v_mfma_f32_16x16x32_bf16 v[14:17], v[2:5], v[18:21], v[14:17]
	ds_read2_b32 v[20:21], v10 offset0:64 offset1:80
	ds_read2_b32 v[22:23], v10 offset0:128 offset1:144
	ds_read2_b32 v[24:25], v10 offset0:192 offset1:208
	ds_read2_b32 v[26:27], v86 offset1:16
	ds_read2_b32 v[84:85], v12 offset0:223 offset1:239
	s_waitcnt lgkmcnt(4)
	v_mov_b32_e32 v19, v20
	s_waitcnt lgkmcnt(3)
	v_add_f32_e32 v13, v20, v22
	s_waitcnt lgkmcnt(2)
	v_add_f32_e32 v18, v13, v24
	s_waitcnt lgkmcnt(1)
	v_mov_b32_e32 v12, v26
	s_waitcnt lgkmcnt(0)
	v_mov_b32_e32 v13, v84
	v_pk_add_f32 v[12:13], v[18:19], v[12:13]
	v_mov_b32_e32 v84, v27
	v_mul_f32_e32 v18, 0x3fb8aa3b, v12
	v_sub_f32_e32 v12, v12, v13
	v_mul_f32_e32 v12, 0x3fb8aa3b, v12
	v_exp_f32_e32 v12, v12
	v_exp_f32_e32 v18, v18
	v_pk_mul_f32 v[16:17], v[16:17], v[12:13] op_sel_hi:[1,0]
	v_pk_mul_f32 v[12:13], v[14:15], v[12:13] op_sel_hi:[1,0]
	v_pk_fma_f32 v[70:71], v[70:71], v[18:19], v[16:17] op_sel_hi:[1,0,1]
	v_pk_fma_f32 v[68:69], v[68:69], v[18:19], v[12:13] op_sel_hi:[1,0,1]
	ds_read_b128 v[12:15], v122 offset:38400
	ds_read_b128 v[16:19], v122 offset:38464
	s_waitcnt lgkmcnt(1)
	v_mfma_f32_16x16x32_bf16 v[12:15], v[6:9], v[12:15], 0
	s_waitcnt lgkmcnt(0)
	v_mfma_f32_16x16x32_bf16 v[12:15], v[2:5], v[16:19], v[12:15]
	v_add_f32_e32 v16, v21, v23
	v_add_f32_e32 v20, v16, v25
	v_pk_add_f32 v[16:17], v[20:21], v[84:85]
	s_nop 0
	v_mul_f32_e32 v18, 0x3fb8aa3b, v16
	v_sub_f32_e32 v16, v16, v17
	v_mul_f32_e32 v16, 0x3fb8aa3b, v16
	v_exp_f32_e32 v16, v16
	v_exp_f32_e32 v18, v18
	v_pk_mul_f32 v[14:15], v[14:15], v[16:17] op_sel_hi:[1,0]
	v_pk_mul_f32 v[12:13], v[12:13], v[16:17] op_sel_hi:[1,0]
	v_pk_fma_f32 v[74:75], v[74:75], v[18:19], v[14:15] op_sel_hi:[1,0,1]
	v_pk_fma_f32 v[72:73], v[72:73], v[18:19], v[12:13] op_sel_hi:[1,0,1]
	ds_read_b128 v[12:15], v122 offset:40704
	ds_read_b128 v[16:19], v122 offset:40768
	s_waitcnt lgkmcnt(1)
	v_mfma_f32_16x16x32_bf16 v[12:15], v[6:9], v[12:15], 0
	s_waitcnt lgkmcnt(0)
	v_mfma_f32_16x16x32_bf16 v[12:15], v[2:5], v[16:19], v[12:15]
	ds_read2_b32 v[16:17], v10 offset0:96 offset1:112
	ds_read2_b32 v[18:19], v10 offset0:160 offset1:176
	ds_read2_b32 v[20:21], v10 offset0:224 offset1:240
	ds_read2_b32 v[22:23], v86 offset0:32 offset1:48
	ds_read2_b32 v[24:25], v11 offset0:127 offset1:143
	s_waitcnt lgkmcnt(4)
	v_mov_b32_e32 v11, v16
	s_waitcnt lgkmcnt(3)
	v_add_f32_e32 v10, v16, v18
	s_waitcnt lgkmcnt(2)
	v_add_f32_e32 v10, v10, v20
	s_waitcnt lgkmcnt(1)
	v_mov_b32_e32 v26, v22
	s_waitcnt lgkmcnt(0)
	v_mov_b32_e32 v27, v24
	v_pk_add_f32 v[10:11], v[10:11], v[26:27]
	v_mov_b32_e32 v24, v23
	v_mul_f32_e32 v16, 0x3fb8aa3b, v10
	v_sub_f32_e32 v10, v10, v11
	v_mul_f32_e32 v10, 0x3fb8aa3b, v10
	v_exp_f32_e32 v10, v10
	v_exp_f32_e32 v16, v16
	v_pk_mul_f32 v[14:15], v[14:15], v[10:11] op_sel_hi:[1,0]
	v_pk_mul_f32 v[10:11], v[12:13], v[10:11] op_sel_hi:[1,0]
	v_pk_fma_f32 v[78:79], v[78:79], v[16:17], v[14:15] op_sel_hi:[1,0,1]
	v_pk_fma_f32 v[76:77], v[76:77], v[16:17], v[10:11] op_sel_hi:[1,0,1]
	ds_read_b128 v[10:13], v122 offset:43008
	s_waitcnt lgkmcnt(0)
	v_mfma_f32_16x16x32_bf16 v[6:9], v[6:9], v[10:13], 0
	ds_read_b128 v[10:13], v122 offset:43072
	s_waitcnt lgkmcnt(0)
	s_barrier
	v_mfma_f32_16x16x32_bf16 v[2:5], v[2:5], v[10:13], v[6:9]
	s_nop 3
	v_add_f32_e32 v6, v17, v19
	v_add_f32_e32 v16, v6, v21
	v_pk_add_f32 v[6:7], v[16:17], v[24:25]
	s_nop 0
	v_mul_f32_e32 v8, 0x3fb8aa3b, v6
	v_sub_f32_e32 v6, v6, v7
	v_mul_f32_e32 v6, 0x3fb8aa3b, v6
	v_exp_f32_e32 v6, v6
	v_exp_f32_e32 v8, v8
	v_pk_mul_f32 v[4:5], v[4:5], v[6:7] op_sel_hi:[1,0]
	v_pk_mul_f32 v[2:3], v[2:3], v[6:7] op_sel_hi:[1,0]
	v_pk_fma_f32 v[82:83], v[82:83], v[8:9], v[4:5] op_sel_hi:[1,0,1]
	v_pk_fma_f32 v[80:81], v[80:81], v[8:9], v[2:3] op_sel_hi:[1,0,1]
	s_cbranch_scc1 .LBB0_938
